# v114 + code placement: one s_nop before GEMM8 and one before GEMM9 so both K-loop heads sit at 0 mod 8 bytes
# speedup vs baseline: 1.0094x; 1.0094x over previous
; template <int GI>
; __device__ __forceinline__ bool sched_next(unsigned char* ws, int i, int G, int c, GUnit& u) {
;     ...
;         constexpr int nwg = d.nM * d.nN;
;         if (L >= nwg) return false;
;         int wgid = L;
;         { constexpr int q = nwg / 8, r = nwg % 8; const int xcd = wgid % 8, off = wgid / 8; wgid = (xcd < r ? xcd * (q + 1) : r * (q + 1) + (xcd - r) * q) + off; }
;         constexpr int nig = 8 * d.nN; const int gid = wgid / nig, fm = gid * 8, gsz = (d.nM - fm) < 8 ? (d.nM - fm) : 8;
;         const int pm = fm + ((wgid % nig) % gsz), pn = (wgid % nig) / gsz;
; template <int GI>
; __device__ __forceinline__ void gemm_phase(LAS unsigned char* lds, unsigned char* ws, int G, int cblk) {
;     ...
;     const int tid = tid_, wid = __builtin_amdgcn_readfirstlane(tid >> 6), lane = tid & 63, wr = wid >> 2, wc = wid & 3, fr = lane & 15, fq = lane >> 4;
;     constexpr int K = g.K, nt = K / BK, lda = g.lda, ldb = g.ldb;
;     unsigned voffA[2], voffB[2];
; #pragma unroll
;     for (int i = 0; i < 2; ++i) { int R, C; stage_rc(tid * 16 + i * 8192, R, C); const int Rb = (R & ~31) + perm32(R & 31);
;         voffA[i] = (unsigned)(R * lda + C) * 2u; voffB[i] = (unsigned)(Rb * ldb + C) * 2u; }
;     const size_t kstep = (size_t)(BK * 2);
;     const size_t hstepA = (size_t)HALF * lda * 2, hstepB = (size_t)HALF * ldb * 2;
;     const unsigned ldsw = (unsigned)wid * 1024u;
;     const int aoff = lds_byte(wr * 64 + fr, fq * 8), boff = lds_byte(wc * 32 + fr, fq * 8);
;     ...
;     GUnit cur, nxt; int ui = 0;
;     if (!sched_next<GI>(ws, 0, G, cblk, cur)) return;
;     f32x4 acc[2][2][4][2];
; #pragma unroll
;     for (int a = 0; a < 2; ++a)
; #pragma unroll
;         for (int b = 0; b < 2; ++b)
; #pragma unroll
;             for (int m = 0; m < 4; ++m)
; #pragma unroll
;                 for (int n = 0; n < 2; ++n) acc[a][b][m][n] = (f32x4){0.f, 0.f, 0.f, 0.f};
;     bf16x8 At[4][2], B0[2][2], B1[2][2];
;     const char* cA = cur.A; const char* cB = cur.B;
;     PG8_STAGE(PG8_SB(0, 0), cB, voffB); PG8_STAGE(PG8_SB(0, 1), cB + hstepB, voffB); PG8_STAGE(PG8_SA(0, 0), cA, voffA); PG8_STAGE(PG8_SA(0, 1), cA + hstepA, voffA);
;     if (wr == 1) PG8_BAR;
;     PG8_WAIT_V(2); PG8_BAR;
;     PG8_STAGE(PG8_SB(1, 0), cB + kstep, voffB); PG8_STAGE(PG8_SA(1, 0), cA + kstep, voffA); PG8_STAGE(PG8_SB(1, 1), cB + hstepB + kstep, voffB);
;     PG8_WAIT_V(6); PG8_BAR;
.LBB0_811:
	s_nop 0
	s_or_b64 exec, exec, s[6:7]
	s_add_u32 s35, s28, 0x16000000
	s_addc_u32 s46, s29, 0
	v_mov_b32_e32 v11, v162
	s_waitcnt lgkmcnt(0)
	s_barrier
	s_cmpk_gt_i32 s2, 0x15ff
	v_readfirstlane_b32 s0, v11
	s_cbranch_scc1 .LBB0_827
	v_lshlrev_b32_e32 v0, 4, v11
	v_add_u32_e32 v1, 0x2000, v0
	v_ashrrev_i32_e32 v2, 31, v1
	v_lshrrev_b32_e32 v2, 22, v2
	v_add_u32_e32 v2, v1, v2
	v_ashrrev_i32_e32 v8, 10, v2
	v_mul_i32_i24_e32 v2, 0x400, v8
	v_sub_u32_e32 v1, v1, v2
	v_lshrrev_b32_e32 v2, 4, v1
	v_bitop3_b32 v1, v2, v1, 32 bitop3:0x6c
	v_ashrrev_i32_e32 v2, 31, v1
	v_lshrrev_b32_e32 v2, 26, v2
	v_add_u32_e32 v2, v1, v2
	v_lshlrev_b32_e32 v3, 3, v8
	v_ashrrev_i32_e32 v9, 6, v2
	v_and_b32_e32 v3, -16, v3
	v_add_u32_e32 v3, v9, v3
	v_and_b32_e32 v4, 3, v9
	s_mov_b32 s6, 0xfffe0
	v_lshrrev_b32_e32 v5, 2, v3
	v_lshlrev_b32_e32 v6, 1, v3
	v_and_b32_e32 v2, 0xc0, v2
	v_and_or_b32 v4, v3, s6, v4
	v_and_b32_e32 v5, 4, v5
	v_and_b32_e32 v6, 24, v6
	v_sub_u32_e32 v1, v1, v2
	v_mov_b32_e32 v2, 1
	v_or3_b32 v4, v4, v5, v6
	v_lshlrev_b32_e32 v5, 5, v8
	v_ashrrev_i16_sdwa v1, v2, sext(v1) dst_sel:DWORD dst_unused:UNUSED_PAD src0_sel:DWORD src1_sel:BYTE_0
	v_and_b32_e32 v5, 32, v5
	v_bfe_i32 v10, v1, 0, 16
	v_add_lshl_u32 v1, v5, v10, 1
	v_lshl_add_u32 v130, v4, 12, v1
	v_lshl_add_u32 v132, v3, 12, v1
	v_bfe_i32 v1, v11, 27, 1
	v_lshrrev_b32_e32 v1, 22, v1
	v_add_u32_e32 v1, v0, v1
	v_and_b32_e32 v1, 0xfffffc00, v1
	v_sub_u32_e32 v0, v0, v1
	v_lshrrev_b32_e32 v1, 4, v0
	v_ashrrev_i32_e32 v3, 31, v11
	v_bitop3_b32 v0, v1, v0, 32 bitop3:0x6c
	v_lshrrev_b32_e32 v3, 26, v3
	v_ashrrev_i32_e32 v1, 31, v0
	v_add_u32_e32 v3, v11, v3
	v_lshrrev_b32_e32 v1, 26, v1
	v_ashrrev_i32_e32 v13, 6, v3
	v_add_u32_e32 v1, v0, v1
	v_lshlrev_b32_e32 v3, 3, v13
	v_ashrrev_i32_e32 v12, 6, v1
	v_and_b32_e32 v3, -16, v3
	v_add_u32_e32 v3, v12, v3
	v_and_b32_e32 v4, 3, v12
	v_and_or_b32 v4, v3, s6, v4
	s_ashr_i32 s6, s2, 31
	s_lshr_b32 s6, s6, 29
	s_add_i32 s6, s2, s6
	s_ashr_i32 s14, s0, 6
	s_ashr_i32 s7, s6, 3
	s_and_b32 s6, s6, -8
	s_ashr_i32 s1, s0, 8
	s_lshl_b32 s26, s14, 10
	s_sub_i32 s6, s2, s6
	s_cmp_lt_i32 s6, 0
	s_movk_i32 s27, 0x2c1
	s_cselect_b32 s8, s27, 0x2c0
	s_mul_i32 s6, s8, s6
	s_add_i32 s6, s6, s7
	s_mul_hi_i32 s7, s6, 0x2e8ba2e9
	s_lshr_b32 s8, s7, 31
	s_ashr_i32 s7, s7, 6
	s_add_i32 s7, s7, s8
	s_lshl_b32 s9, s7, 3
	s_mulk_i32 s7, 0x160
	s_sub_i32 s6, s6, s7
	s_sext_i32_i16 s7, s6
	s_bfe_u32 s7, s7, 0x3001c
	s_add_i32 s7, s6, s7
	s_sext_i32_i16 s8, s7
	s_and_b32 s7, s7, 0xfff8
	s_sub_i32 s6, s6, s7
	s_sext_i32_i16 s6, s6
	s_add_i32 s6, s9, s6
	s_ashr_i32 s7, s6, 31
	s_lshr_b32 s8, s8, 3
	s_lshl_b64 s[12:13], s[6:7], 20
	s_add_u32 s40, s3, s12
	s_addc_u32 s41, s54, s13
	v_lshrrev_b32_e32 v5, 2, v3
	v_lshlrev_b32_e32 v6, 1, v3
	v_and_b32_e32 v1, 0xc0, v1
	s_add_u32 s47, s28, 0x4200000
	v_and_b32_e32 v5, 4, v5
	v_and_b32_e32 v6, 24, v6
	v_sub_u32_e32 v0, v0, v1
	s_addc_u32 s48, s29, 0
	s_bfe_i64 s[12:13], s[8:9], 0x100000
	v_or3_b32 v4, v4, v5, v6
	v_lshlrev_b32_e32 v5, 5, v13
	v_ashrrev_i16_sdwa v0, v2, sext(v0) dst_sel:DWORD dst_unused:UNUSED_PAD src0_sel:DWORD src1_sel:BYTE_0
	s_lshl_b64 s[8:9], s[12:13], 20
	v_and_b32_e32 v5, 32, v5
	v_bfe_i32 v14, v0, 0, 16
	s_add_u32 s42, s47, s8
	v_add_lshl_u32 v0, v5, v14, 1
	s_addc_u32 s43, s48, s9
	s_add_i32 s49, s26, 0
	v_lshl_add_u32 v134, v4, 12, v0
	s_add_i32 m0, s49, 0x10000
	v_lshl_add_u32 v136, v3, 12, v0
	global_load_lds_dwordx4 v134, s[42:43]
	s_add_i32 m0, s49, 0x12000
	s_add_u32 s8, s42, 0x80000
	global_load_lds_dwordx4 v130, s[42:43]
	s_addc_u32 s9, s43, 0
	s_add_i32 m0, s49, 0x14000
	s_add_i32 s50, s49, 0x2000
	global_load_lds_dwordx4 v134, s[8:9]
	s_add_i32 m0, s49, 0x16000
	v_mov_b32_e32 v139, 0
	global_load_lds_dwordx4 v130, s[8:9]
	s_mov_b32 m0, s49
	s_add_u32 s8, s40, 0x80000
	global_load_lds_dwordx4 v136, s[40:41]
	s_mov_b32 m0, s50
	s_addc_u32 s9, s41, 0
	s_add_i32 s51, s49, 0x4000
	global_load_lds_dwordx4 v132, s[40:41]
	s_mov_b32 m0, s51
	s_add_i32 s52, s49, 0x6000
	global_load_lds_dwordx4 v136, s[8:9]
	s_mov_b32 m0, s52
	v_mov_b32_e32 v135, v139
	global_load_lds_dwordx4 v132, s[8:9]
	v_mov_b32_e32 v131, v139
	v_mov_b32_e32 v137, v139
	v_mov_b32_e32 v133, v139
	s_cmp_eq_u32 s1, 1
	s_mov_b32 s7, 0
	v_lshl_add_u64 v[6:7], s[42:43], 0, v[134:135]
	v_lshl_add_u64 v[4:5], s[42:43], 0, v[130:131]
	v_lshl_add_u64 v[0:1], s[40:41], 0, v[136:137]
	s_cselect_b64 s[8:9], -1, 0
	s_cmp_lg_u32 s1, 1
	v_lshl_add_u64 v[2:3], s[40:41], 0, v[132:133]
	s_cbranch_scc1 .LBB0_814
	s_barrier

; template <int GI>
; __device__ __forceinline__ bool sched_next(unsigned char* ws, int i, int G, int c, GUnit& u) {
;     ...
;         { constexpr int q = nwg / 8, r = nwg % 8; const int xcd = wgid % 8, off = wgid / 8; wgid = (xcd < r ? xcd * (q + 1) : r * (q + 1) + (xcd - r) * q) + off; }
;         constexpr int nig = 8 * d.nN; const int gid = wgid / nig, fm = gid * 8, gsz = (d.nM - fm) < 8 ? (d.nM - fm) : 8;
;         const int pm = fm + ((wgid % nig) % gsz), pn = (wgid % nig) / gsz;
; template <int GI>
; __device__ __forceinline__ void gemm_phase(LAS unsigned char* lds, unsigned char* ws, int G, int cblk) {
;     ...
;     GUnit cur, nxt; int ui = 0;
;     if (!sched_next<GI>(ws, 0, G, cblk, cur)) return;
.LBB0_879:
	s_nop 0
	s_or_b64 exec, exec, s[6:7]
	s_waitcnt lgkmcnt(0)
	s_barrier
	s_and_b64 vcc, exec, s[10:11]
	v_readfirstlane_b32 s14, v162
	s_cbranch_vccnz .LBB0_903
	s_ashr_i32 s0, s2, 31
	s_lshr_b32 s0, s0, 29
	s_add_i32 s3, s2, s0
	s_and_b32 s0, s3, -8
	s_sub_i32 s0, s2, s0
	s_cmp_gt_i32 s0, -1
	s_cbranch_scc0 .LBB0_882
	s_lshl_b32 s1, s0, 7
	s_ashr_i32 s3, s3, 3
	s_cbranch_execz .LBB0_883
	s_branch .LBB0_884
